# v143 + SSD conv arithmetic: 37 v_pk_mul_f32 + add pairs rewritten as f32 v_fma_f32 (same operands/order, fused), 11 operand-assembly moves removed
# speedup vs baseline: 1.0080x; 1.0014x over previous
.LBB0_224:
	s_or_b64 exec, exec, s[4:5]
	v_lshlrev_b64 v[52:53], 2, v[52:53]
	v_add_u32_e32 v233, 0x8000, v52
	ds_read_b128 v[114:117], v233 offset:49168
	ds_read_b128 v[122:125], v233 offset:49152
	ds_read_b128 v[126:129], v233 offset:16
	ds_read_b128 v[130:133], v233
	s_mov_b64 s[38:39], 0x3000
	ds_read_b128 v[134:137], v233 offset:12288
	s_nop 0
	ds_read_b128 v[138:141], v233 offset:12304
	s_movk_i32 s4, 0x6000
	s_mov_b64 s[40:41], 0x6000
	s_mov_b64 s[48:49], 0x9000
	s_mov_b32 s5, 0x9000
	s_cmp_lt_i32 s20, 40
	s_waitcnt lgkmcnt(2)
	s_waitcnt lgkmcnt(1)
	v_mov_b32_e32 v119, v134
	v_mov_b32_e32 v134, v131
	v_fma_f32 v0, v130, v38, v122
	v_fma_f32 v0, v119, v39, v0
	s_waitcnt lgkmcnt(0)
	v_mov_b32_e32 v38, v138
	v_mov_b32_e32 v39, v126
	v_mov_b32_e32 v126, v139
	v_fma_f32 v39, v39, v103, v114
	v_fma_f32 v11, v127, v11, v115
	v_fma_f32 v118, v38, v102, v39
	v_pk_mul_f32 v[38:39], v[134:135], v[106:107]
	v_fma_f32 v107, v139, v10, v11
	v_mov_b32_e32 v10, v132
	v_mov_b32_e32 v11, v136
	v_mov_b32_e32 v136, v133
	v_fma_f32 v10, v10, v40, v124
	v_fma_f32 v119, v11, v41, v10
	v_mov_b32_e32 v10, v140
	v_mov_b32_e32 v11, v128
	v_mov_b32_e32 v128, v141
	v_fma_f32 v11, v11, v99, v116
	v_fma_f32 v122, v10, v98, v11
	v_add_f32_e32 v38, v123, v38
	v_fma_f32 v10, v133, v100, v125
	v_fma_f32 v123, v137, v101, v10
	v_add_f32_e32 v106, v38, v39
	v_fma_f32 v11, v129, v13, v117
	v_fma_f32 v124, v141, v12, v11
	s_nop 0
	ds_read_b128 v[10:13], v233 offset:24576
	s_nop 0
	ds_read_b128 v[38:41], v233 offset:24592
	ds_read_b128 v[98:101], v233 offset:36864
	ds_read_b128 v[114:117], v233 offset:36880
	s_waitcnt lgkmcnt(3)
	s_waitcnt lgkmcnt(1)
	v_mov_b32_e32 v53, v98
	v_mov_b32_e32 v98, v11
	v_fma_f32 v0, v10, v46, v0
	v_fma_f32 v0, v53, v47, v0
	s_waitcnt lgkmcnt(0)
	v_mov_b32_e32 v46, v114
	v_mov_b32_e32 v47, v38
	v_fma_f32 v10, v47, v111, v118
	v_fma_f32 v46, v46, v110, v10
	s_nop 0
	v_fma_f32 v10, v98, v112, v106
	v_fma_f32 v47, v99, v113, v10
	s_nop 0
	v_fma_f32 v11, v39, v43, v107
	v_fma_f32 v38, v115, v42, v11
	v_mov_b32_e32 v10, v12
	v_mov_b32_e32 v11, v100
	v_fma_f32 v10, v10, v48, v119
	v_fma_f32 v12, v11, v49, v10
	v_mov_b32_e32 v10, v116
	v_mov_b32_e32 v11, v40
	v_mov_b32_e32 v40, v117
	v_fma_f32 v11, v11, v105, v122
	v_fma_f32 v39, v10, v104, v11
	s_nop 0
	v_fma_f32 v10, v13, v108, v123
	v_fma_f32 v13, v101, v109, v10
	v_pk_mul_f32 v[10:11], v[40:41], v[44:45]
	v_mul_f32_e32 v40, 0xbfb8aa3b, v12
	v_exp_f32_e32 v40, v40
	v_mul_f32_e32 v41, 0xbfb8aa3b, v38
	v_exp_f32_e32 v41, v41
	v_add_f32_e32 v11, v11, v124
	v_add_f32_e32 v40, 1.0, v40
	v_rcp_f32_e32 v40, v40
	v_add_f32_e32 v41, 1.0, v41
	v_rcp_f32_e32 v41, v41
	v_add_f32_e32 v10, v10, v11
	v_mul_f32_e32 v11, 0xbfb8aa3b, v0
	v_mul_f32_e32 v12, v12, v40
	v_mul_f32_e32 v40, 0xbfb8aa3b, v13
	v_exp_f32_e32 v11, v11
	v_exp_f32_e32 v40, v40
	v_mul_f32_e32 v38, v38, v41
	v_mul_f32_e32 v41, 0xbfb8aa3b, v39
	v_exp_f32_e32 v41, v41
	v_add_f32_e32 v11, 1.0, v11
	v_add_f32_e32 v40, 1.0, v40
	v_rcp_f32_e32 v11, v11
	v_rcp_f32_e32 v40, v40
	v_add_f32_e32 v41, 1.0, v41
	v_rcp_f32_e32 v41, v41
	v_mul_f32_e32 v0, v0, v11
	v_mul_f32_e32 v11, 0xbfb8aa3b, v47
	v_mul_f32_e32 v13, v13, v40
	v_mul_f32_e32 v40, 0xbfb8aa3b, v46
	v_exp_f32_e32 v11, v11
	v_exp_f32_e32 v40, v40
	v_mul_f32_e32 v39, v39, v41
	v_mul_f32_e32 v41, 0xbfb8aa3b, v10
	v_exp_f32_e32 v41, v41
	v_add_f32_e32 v11, 1.0, v11
	v_add_f32_e32 v40, 1.0, v40
	v_rcp_f32_e32 v11, v11
	v_rcp_f32_e32 v40, v40
	v_add_f32_e32 v41, 1.0, v41
	v_rcp_f32_e32 v41, v41
	v_mul_f32_e32 v11, v47, v11
	v_mul_f32_e32 v40, v46, v40
	v_lshlrev_b64 v[46:47], 2, v[50:51]
	v_add_u32_e32 v233, 0x8000, v46
	v_lshl_add_u64 v[98:99], s[8:9], 0, v[46:47]
	v_mul_f32_e32 v41, v10, v41
	v_cvt_pk_bf16_f32 v10, v0, v11
	v_cvt_pk_bf16_f32 v11, v12, v13
	v_cvt_pk_bf16_f32 v12, v40, v38
	v_cvt_pk_bf16_f32 v13, v39, v41
	ds_read_b128 v[38:41], v233 offset:49168
	s_nop 0
	ds_read_b128 v[42:45], v233 offset:49152
	s_nop 0
	ds_read_b128 v[46:49], v233 offset:16
	ds_read_b128 v[50:53], v233
	ds_read_b128 v[102:105], v233 offset:12288
	s_nop 0
	ds_read_b128 v[106:109], v233 offset:12304
	s_waitcnt lgkmcnt(2)
	s_waitcnt lgkmcnt(1)
	v_mov_b32_e32 v101, v102
	v_mov_b32_e32 v102, v51
	v_fma_f32 v0, v50, v34, v42
	v_fma_f32 v100, v101, v35, v0
	s_waitcnt lgkmcnt(0)
	v_mov_b32_e32 v34, v106
	v_mov_b32_e32 v35, v46
	v_fma_f32 v0, v35, v95, v38
	v_fma_f32 v94, v34, v94, v0
	v_fma_f32 v0, v51, v96, v43
	v_fma_f32 v51, v103, v97, v0
	v_fma_f32 v0, v47, v31, v39
	v_fma_f32 v50, v107, v30, v0
	v_mov_b32_e32 v30, v52
	v_mov_b32_e32 v31, v104
	v_mov_b32_e32 v104, v53
	v_fma_f32 v0, v30, v36, v44
	v_fma_f32 v0, v31, v37, v0
	v_mov_b32_e32 v30, v108
	v_mov_b32_e32 v31, v48
	v_fma_f32 v31, v31, v91, v40
	v_fma_f32 v46, v30, v90, v31
	v_fma_f32 v30, v53, v92, v45
	v_fma_f32 v47, v105, v93, v30
	v_fma_f32 v31, v49, v33, v41
	s_nop 0
	v_fma_f32 v48, v109, v32, v31
	ds_read_b128 v[34:37], v233 offset:24576
	s_nop 0
	ds_read_b128 v[30:33], v233 offset:24592
	s_nop 0
	ds_read_b128 v[38:41], v233 offset:36864
	s_nop 0
	ds_read_b128 v[42:45], v233 offset:36880
	s_waitcnt lgkmcnt(3)
	v_mov_b32_e32 v52, v34
	s_waitcnt lgkmcnt(1)
	v_mov_b32_e32 v53, v38
	v_fma_f32 v26, v34, v26, v100
	v_fma_f32 v34, v53, v27, v26
	s_waitcnt lgkmcnt(0)
	v_mov_b32_e32 v26, v42
	v_mov_b32_e32 v27, v30
	v_fma_f32 v27, v27, v89, v94
	v_fma_f32 v42, v26, v88, v27
	v_fma_f32 v26, v35, v86, v51
	v_fma_f32 v23, v31, v23, v50
	v_fma_f32 v26, v39, v87, v26
	v_fma_f32 v27, v43, v22, v23
	v_mov_b32_e32 v22, v36
	v_mov_b32_e32 v23, v40
	v_fma_f32 v0, v22, v28, v0
	v_fma_f32 v0, v23, v29, v0
	v_mov_b32_e32 v22, v44
	v_mov_b32_e32 v23, v32
	v_mov_b32_e32 v32, v45
	v_fma_f32 v23, v23, v83, v46
	v_fma_f32 v28, v22, v82, v23
	s_nop 0
	v_fma_f32 v22, v37, v84, v47
	v_fma_f32 v29, v41, v85, v22
	v_pk_mul_f32 v[22:23], v[32:33], v[24:25]
	v_mul_f32_e32 v25, 0xbfb8aa3b, v0
	v_exp_f32_e32 v25, v25
	v_mul_f32_e32 v24, 0xbfb8aa3b, v26
	v_exp_f32_e32 v24, v24
	v_add_f32_e32 v23, v23, v48
	v_add_f32_e32 v25, 1.0, v25
	v_rcp_f32_e32 v25, v25
	v_add_f32_e32 v24, 1.0, v24
	v_rcp_f32_e32 v24, v24
	v_add_f32_e32 v22, v22, v23
	v_mul_f32_e32 v0, v0, v25
	v_mul_f32_e32 v25, 0xbfb8aa3b, v29
	v_exp_f32_e32 v25, v25
	v_mul_f32_e32 v24, v26, v24
	v_mul_f32_e32 v26, 0xbfb8aa3b, v42
	v_mul_f32_e32 v23, 0xbfb8aa3b, v34
	v_add_f32_e32 v25, 1.0, v25
	v_rcp_f32_e32 v25, v25
	v_exp_f32_e32 v26, v26
	v_exp_f32_e32 v23, v23
	v_mul_f32_e32 v25, v29, v25
	v_mul_f32_e32 v29, 0xbfb8aa3b, v27
	v_exp_f32_e32 v29, v29
	v_add_f32_e32 v26, 1.0, v26
	v_add_f32_e32 v23, 1.0, v23
	v_rcp_f32_e32 v26, v26
	v_add_f32_e32 v29, 1.0, v29
	v_rcp_f32_e32 v29, v29
	v_rcp_f32_e32 v23, v23
	v_mul_f32_e32 v26, v42, v26
	v_mul_f32_e32 v27, v27, v29
	v_mul_f32_e32 v29, 0xbfb8aa3b, v28
	v_exp_f32_e32 v29, v29
	v_mul_f32_e32 v23, v34, v23
	v_add_f32_e32 v29, 1.0, v29
	v_rcp_f32_e32 v29, v29
	s_nop 0
	v_mul_f32_e32 v28, v28, v29
	v_mul_f32_e32 v29, 0xbfb8aa3b, v22
	v_exp_f32_e32 v29, v29
	s_nop 0
	v_add_f32_e32 v29, 1.0, v29
	v_rcp_f32_e32 v29, v29
	s_nop 0
	v_mul_f32_e32 v29, v22, v29
	v_cvt_pk_bf16_f32 v22, v23, v24
	v_cvt_pk_bf16_f32 v24, v26, v27
	v_lshlrev_b64 v[26:27], 2, v[76:77]
	v_add_u32_e32 v233, 0x8000, v26
	v_cvt_pk_bf16_f32 v23, v0, v25
	v_cvt_pk_bf16_f32 v25, v28, v29
	ds_read_b128 v[28:31], v233 offset:49168
	ds_read_b128 v[40:43], v233 offset:49152
	ds_read_b128 v[44:47], v233 offset:16
	ds_read_b128 v[48:51], v233
	ds_read_b128 v[82:85], v233 offset:12288
	ds_read_b128 v[86:89], v233 offset:12304
	s_waitcnt lgkmcnt(2)
	s_waitcnt lgkmcnt(1)
	v_mov_b32_e32 v33, v82
	v_mov_b32_e32 v82, v49
	v_fma_f32 v0, v48, v18, v40
	v_fma_f32 v40, v33, v19, v0
	s_waitcnt lgkmcnt(0)
	v_mov_b32_e32 v18, v86
	v_mov_b32_e32 v19, v44
	v_mov_b32_e32 v44, v87
	v_fma_f32 v0, v19, v79, v28
	v_fma_f32 v39, v18, v78, v0
	v_fma_f32 v0, v49, v80, v41
	v_fma_f32 v38, v83, v81, v0
	v_fma_f32 v0, v45, v15, v29
	v_fma_f32 v37, v87, v14, v0
	v_mov_b32_e32 v14, v50
	v_mov_b32_e32 v15, v84
	v_mov_b32_e32 v84, v51
	v_fma_f32 v0, v14, v20, v42
	v_fma_f32 v36, v15, v21, v0
	v_mov_b32_e32 v14, v88
	v_mov_b32_e32 v15, v46
	v_mov_b32_e32 v46, v89
	v_fma_f32 v0, v15, v73, v30
	v_fma_f32 v35, v14, v72, v0
	s_nop 0
	v_fma_f32 v0, v51, v74, v43
	v_fma_f32 v34, v85, v75, v0
	v_fma_f32 v0, v47, v17, v31
	s_nop 0
	v_fma_f32 v0, v89, v16, v0
	ds_read_b128 v[18:21], v233 offset:24576
	s_nop 0
	ds_read_b128 v[14:17], v233 offset:24592
	ds_read_b128 v[26:29], v233 offset:36864
	s_nop 0
	ds_read_b128 v[30:33], v233 offset:36880
	s_barrier
	s_waitcnt lgkmcnt(3)
	v_mov_b32_e32 v42, v18
	s_waitcnt lgkmcnt(1)
	v_mov_b32_e32 v43, v26
	v_pk_mul_f32 v[6:7], v[42:43], v[6:7]
	v_mov_b32_e32 v26, v19
	v_add_f32_e32 v6, v40, v6
	v_add_f32_e32 v18, v6, v7
	s_waitcnt lgkmcnt(0)
	v_mov_b32_e32 v6, v30
	v_mov_b32_e32 v7, v14
	v_pk_mul_f32 v[6:7], v[6:7], v[70:71]
	v_mov_b32_e32 v14, v31
	v_add_f32_e32 v7, v7, v39
	v_add_f32_e32 v30, v6, v7
	v_pk_mul_f32 v[6:7], v[26:27], v[68:69]
	v_pk_mul_f32 v[2:3], v[14:15], v[2:3]
	v_add_f32_e32 v6, v38, v6
	v_add_f32_e32 v3, v3, v37
	v_add_f32_e32 v6, v6, v7
	v_add_f32_e32 v7, v2, v3
	v_mov_b32_e32 v2, v20
	v_mov_b32_e32 v3, v28
	v_pk_mul_f32 v[2:3], v[2:3], v[8:9]
	v_mov_b32_e32 v28, v21
	v_add_f32_e32 v2, v36, v2
	v_add_f32_e32 v8, v2, v3
	v_mov_b32_e32 v2, v32
	v_mov_b32_e32 v3, v16
	v_pk_mul_f32 v[2:3], v[2:3], v[66:67]
	v_mov_b32_e32 v16, v33
	v_add_f32_e32 v3, v3, v35
	v_add_f32_e32 v9, v2, v3
	v_pk_mul_f32 v[2:3], v[28:29], v[64:65]
	s_nop 0
	v_add_f32_e32 v2, v34, v2
	v_add_f32_e32 v14, v2, v3
	v_pk_mul_f32 v[2:3], v[16:17], v[4:5]
	v_mul_f32_e32 v4, 0xbfb8aa3b, v8
	v_exp_f32_e32 v4, v4
	v_add_f32_e32 v0, v3, v0
	v_mul_f32_e32 v3, 0xbfb8aa3b, v6
	v_exp_f32_e32 v3, v3
	v_add_f32_e32 v4, 1.0, v4
	v_rcp_f32_e32 v4, v4
	v_add_f32_e32 v0, v2, v0
	v_add_f32_e32 v3, 1.0, v3
	v_rcp_f32_e32 v3, v3
	v_mul_f32_e32 v4, v8, v4
	v_mul_f32_e32 v8, 0xbfb8aa3b, v7
	v_exp_f32_e32 v8, v8
	v_mul_f32_e32 v2, 0xbfb8aa3b, v18
	v_mul_f32_e32 v3, v6, v3
	v_mul_f32_e32 v6, 0xbfb8aa3b, v30
	v_add_f32_e32 v8, 1.0, v8
	v_rcp_f32_e32 v8, v8
	v_exp_f32_e32 v2, v2
	v_mul_f32_e32 v5, 0xbfb8aa3b, v14
	v_exp_f32_e32 v6, v6
	v_mul_f32_e32 v7, v7, v8
	v_mul_f32_e32 v8, 0xbfb8aa3b, v9
	v_exp_f32_e32 v8, v8
	v_exp_f32_e32 v5, v5
	v_add_f32_e32 v2, 1.0, v2
	v_add_f32_e32 v6, 1.0, v6
	v_add_f32_e32 v8, 1.0, v8
	v_rcp_f32_e32 v8, v8
	v_rcp_f32_e32 v2, v2
	v_add_f32_e32 v5, 1.0, v5
	v_rcp_f32_e32 v6, v6
	v_mul_f32_e32 v8, v9, v8
	v_mul_f32_e32 v9, 0xbfb8aa3b, v0
	v_exp_f32_e32 v9, v9
	v_rcp_f32_e32 v5, v5
	v_mul_f32_e32 v2, v18, v2
	v_mul_f32_e32 v6, v30, v6
	v_add_f32_e32 v9, 1.0, v9
	v_rcp_f32_e32 v9, v9
	v_mul_f32_e32 v5, v14, v5
	v_cvt_pk_bf16_f32 v2, v2, v3
	v_cvt_pk_bf16_f32 v3, v4, v5
	v_mul_f32_e32 v0, v0, v9
	v_cvt_pk_bf16_f32 v4, v6, v7
	v_add_u32_e32 v6, s19, v54
	v_cvt_pk_bf16_f32 v5, v8, v0
	v_ashrrev_i32_e32 v7, 31, v6
	v_lshlrev_b32_e32 v0, 1, v56
	s_cbranch_scc1 .LBB0_226
	v_lshlrev_b64 v[8:9], 10, v[6:7]
	v_lshl_add_u64 v[8:9], s[14:15], 0, v[8:9]
	s_add_i32 s88, s22, 0xfffff600
	v_lshl_add_u64 v[8:9], s[88:89], 1, v[8:9]
	v_lshl_add_u64 v[8:9], v[8:9], 0, v[0:1]
	global_store_dwordx4 v[8:9], v[10:13], off
